# v128 + out-proj residual-stream stores write-through and no leader write-back at the barrier after layer 0's out-proj (fence elision at P0, norm and out-proj barriers)
# baseline (speedup 1.0000x reference)
; __device__ __forceinline__ unsigned xb_add(unsigned* p, unsigned v) { return __hip_atomic_fetch_add(p, v, __ATOMIC_RELAXED, __HIP_MEMORY_SCOPE_AGENT); }
; #define GRID_BARRIER() do { XcdBarrier xb_; xb_.bar = (unsigned*)(a.ws + WS_BAR); xb_.x = xb_xcc_id(); xb_.st = (volatile LAS unsigned*)(lds + 131072) + 8; xcd_barrier(xb_); } while (0)
; __device__ __forceinline__ void xcd_barrier(const XcdBarrier& b) {
;     asm volatile("s_waitcnt vmcnt(0)" ::: "memory");
;     __syncthreads();
;     if (threadIdx.x == 0) {
;         unsigned* bar = b.bar;
;         __builtin_amdgcn_s_waitcnt(0);
;         unsigned nloc = b.st[0], nx = b.st[1];
;         if (nloc == 0u) { xcd_barrier_complete(bar, b.x, nloc, nx); b.st[0] = nloc; b.st[1] = nx; }
;         const unsigned old = xb_add(&bar[XB_XSUB(b.x)], 1u);
;         const unsigned gen = old / nloc;
;         if (old + 1u == (gen + 1u) * nloc) {
;             __builtin_amdgcn_fence(__ATOMIC_RELEASE, "agent");
;             asm volatile("s_waitcnt vmcnt(0)" ::: "memory");
;             const unsigned og = xb_add(&bar[XB_TOP], 1u);
;             const unsigned tg = og / nx;
;             if (og + 1u == (tg + 1u) * nx) xb_add(&bar[XB_TOPGEN], 1u);
; __global__ void __launch_bounds__(512, 2) fwd_megakernel(Args a) {
;     ...
;         if (l == 0) GRID_BARRIER();
.LBB0_683:
	v_readlane_b32 s2, v255, 11
	v_readlane_b32 s3, v255, 12
	s_mov_b64 s[0:1], -1
	s_and_b64 vcc, exec, s[2:3]
	v_readlane_b32 s12, v255, 6
	s_mov_b64 s[26:27], 0x1000
	v_readlane_b32 s13, v255, 7
	s_cbranch_vccz .LBB0_190
	s_getreg_b32 s2, hwreg(HW_REG_XCC_ID, 0, 4)
	s_waitcnt vmcnt(0)
	s_barrier
	s_mov_b64 s[0:1], exec
	v_readlane_b32 s4, v253, 2
	v_readlane_b32 s5, v253, 3
	s_and_b64 s[4:5], s[0:1], s[4:5]
	s_mov_b64 exec, s[4:5]
	s_cbranch_execz .LBB0_189
	v_mov_b32_e32 v0, 0x20020
	s_waitcnt vmcnt(0) lgkmcnt(0)
	ds_read2_b32 v[2:3], v0 offset1:1
	s_and_b32 s3, s2, 15
	s_lshl_b32 s3, s3, 8
	s_add_u32 s6, s78, 0x1701400
	s_addc_u32 s7, s79, 0
	s_add_u32 s6, s6, s3
	s_addc_u32 s7, s7, 0
	s_add_u32 s8, s6, 0x1000
	s_addc_u32 s9, s7, 0
	s_add_u32 s10, s78, 0x1703400
	s_addc_u32 s11, s79, 0
	s_waitcnt lgkmcnt(0)
	v_readfirstlane_b32 s30, v2
	v_readfirstlane_b32 s31, v3
	s_nop 3
	s_cmp_eq_u32 s30, 0
	s_cbranch_scc1 .Lxb_slow_o
	s_mov_b32 s29, 4
	global_atomic_add v2, v173, v212, s[6:7] sc0
	buffer_inv sc1
	s_add_i32 s32, s29, 1
	s_mul_i32 s5, s32, s30
	s_mul_i32 s32, s32, s31
	s_waitcnt vmcnt(1)
	v_readfirstlane_b32 s3, v2
	s_nop 3
	s_add_i32 s3, s3, 1
	s_cmp_lg_u32 s3, s5
	s_cbranch_scc1 .Lxb_local_o
	global_atomic_add v173, v212, s[10:11]
	s_mov_b32 s3, 0
